# stack3 + diff attention steady loop: half-step stagger between wave halves (waves 4-7 barrier between max and PV phase; LDS-DMA issued right after each barrier, drained before the next)
# speedup vs baseline: 1.0133x; 1.0133x over previous
; #define WAIT_BAR(N) asm volatile("s_waitcnt vmcnt(" #N ") lgkmcnt(0)\n\ts_barrier":::"memory")
;   #define DMA_K(t,slot) glds16(ksrc+(long)(t)*KVBLK*DMI,(unsigned)__builtin_amdgcn_readfirstlane(kdst+(slot)))
;   #define DMA_V(t,slot) glds16(vsrc+(long)(t)*KVBLK*DMI,(unsigned)__builtin_amdgcn_readfirstlane(vdst+(slot)))
;   #define BIASADD(P0,P1,t) do{ if(BIAS){ const lds_fptr bp_=biasl+KVBLK*(t); _Pragma("unroll") for(int i_=0;i_<4;++i_){ \
;       const f32x4_t b0_=*(const __attribute__((address_space(3))) f32x4_t*)(bp_+8*i_), b1_=*(const __attribute__((address_space(3))) f32x4_t*)(bp_+32+8*i_); \
;       _Pragma("unroll") for(int j_=0;j_<4;++j_){ P0[4*i_+j_]+=b0_[j_]; P1[4*i_+j_]+=b1_[j_]; } } } }while(0)
;   #define CMASK(P0,P1,t) do{int jb_=(t)-(NT-4); if(jb_>=0)cmask(P0,P1,jb_,qrel,hi);}while(0)
;   #define START(P0,P1) do{ const float rm=rowmax(P0,P1); resc=false; \
;     { const float dl=rm; mhat=fadd_s(mhat,dl); \
;       _Pragma("unroll") for(int r=0;r<16;++r){P0[r]=fsub_s(P0[r],dl);P1[r]=fsub_s(P1[r],dl);} \
;       _Pragma("unroll") for(int r=0;r<16;++r)negm[r]=-mhat; asm volatile("":"+v"(negm)); } \
;     _Pragma("unroll") for(int r=0;r<16;++r)P0[r]=__builtin_amdgcn_exp2f(P0[r]); }while(0)
;   #define ROT() do{sl_prev=sl_cur;sl_cur=sl_next;sl_next=(sl_next==(NSLOT-1)*SLOTB)?0:sl_next+SLOTB;}while(0)
;   #define CMASK(P0,P1,t) do{}while(0)
;   #define CMASK(P0,P1,t) do{int jb_=(t)-(NT-4); if(jb_>=0)cmask(P0,P1,jb_,qrel,hi);}while(0)
; #define WAIT_BAR(N) asm volatile("s_waitcnt vmcnt(" #N ") lgkmcnt(0)\n\ts_barrier":::"memory")
; template<int THRL,bool BIAS> __device__ __forceinline__ void attn_unit(int b,int qb,const bf16*Q,const bf16*__restrict__ K,const bf16*__restrict__ V,bf16*O,const float*__restrict__ biasg,char*shm,const int tid_in,const bool comb,const bf16*O0,const float lam,const float osc,const float*__restrict__ ...
;     ...
;   f32x16 pA0,pA1,pB0,pB1;
;   int sl_prev=0,sl_cur=0,sl_next=SLOTB;
;     ...
;   DMA_K(2,2*SLOTB);
;   WAIT_BAR(3);
;   qkt(pA0,pA1,Kbase,qr,negm,r32,hi);asm volatile("s_nop 15\n\ts_nop 7":"+v"(pA0),"+v"(pA1));BIASADD(pA0,pA1,0);CMASK(pA0,pA1,0);
;   START(pA0,pA1);
;   _Pragma("unroll") for(int r=0;r<16;++r)pA1[r]=__builtin_amdgcn_exp2f(pA1[r]);
;   WAIT_BAR(0);
;   DMA_K(3,0);DMA_V(1,SLOTB);
;   ROT();
;   kload8(kf,kp0+sl_cur);
;   WAIT_BAR(3);
;   s16x4 vlo[3],vhi[3]; u32x4 pw0,pw1,pw2,pw3;
.LBB0_278:
	v_lshlrev_b32_e32 v0, 1, v34
	v_and_b32_e32 v248, 32, v0
	v_lshlrev_b32_e32 v0, 4, v34
	v_and_b32_e32 v0, 0xc0, v0
	v_lshl_or_b32 v240, v232, 8, v0
	v_add_u32_e32 v0, 0, v248
	v_add3_u32 v245, v0, v242, v240
	v_max3_f32 v0, v18, v19, v2
	v_max3_f32 v34, v20, v21, v3
	s_and_b32 s5, s5, 0x3fffffc0
	v_max3_f32 v0, v0, v4, v5
	v_max3_f32 v34, v34, v24, v25
	s_lshl_b32 s5, s5, 2
	v_max3_f32 v0, v0, v22, v23
	v_max3_f32 v34, v34, v8, v9
	s_add_i32 s62, s5, 0
	v_max3_f32 v0, v0, v6, v7
	v_max3_f32 v34, v34, v28, v29
	s_add_i32 s62, s62, 0x12000
	v_max3_f32 v0, v0, v26, v27
	v_max3_f32 v34, v34, v12, v13
	s_cmp_lg_u32 0, -1
	v_max3_f32 v0, v0, v10, v11
	v_max3_f32 v34, v34, v32, v33
	s_mov_b32 s6, 1
	v_max3_f32 v0, v0, v30, v31
	v_max3_f32 v34, v34, v16, v17
	s_mov_b32 s76, 0
	v_max3_f32 v0, v0, v14, v15
	v_lshlrev_b32_e32 v230, 4, v232
	v_max_f32_e32 v0, v0, v34
	v_lshl_add_u32 v241, v252, 2, s62
	v_mov_b32_e32 v34, v0
	s_nop 1
	v_permlane32_swap_b32_e32 v0, v34
	v_max_f32_e32 v0, v0, v34
	s_nop 0
	v_add_f32_e32 v224, v1, v0
	v_sub_f32_e32 v2, v2, v0
	v_sub_f32_e32 v3, v3, v0
	v_sub_f32_e32 v18, v18, v0
	v_sub_f32_e32 v19, v19, v0
	v_sub_f32_e32 v20, v20, v0
	s_nop 0
	v_xor_b32_e32 v80, 0x80000000, v224
	v_mov_b32_e32 v81, v80
	v_mov_b32_e32 v82, v80
	v_mov_b32_e32 v83, v80
	v_mov_b32_e32 v84, v80
	v_mov_b32_e32 v85, v80
	v_mov_b32_e32 v86, v80
	v_mov_b32_e32 v87, v80
	v_mov_b32_e32 v88, v80
	v_mov_b32_e32 v89, v80
	v_mov_b32_e32 v90, v80
	v_mov_b32_e32 v91, v80
	v_mov_b32_e32 v92, v80
	v_mov_b32_e32 v93, v80
	v_mov_b32_e32 v94, v80
	v_mov_b32_e32 v95, v80
	s_waitcnt vmcnt(0) lgkmcnt(0)
	s_barrier
	v_exp_f32_e32 v96, v2
	v_exp_f32_e32 v97, v3
	v_lshl_add_u64 v[2:3], v[234:235], 0, s[50:51]
	s_mov_b32 s5, m0
	s_mov_b32 m0, s64
	s_nop 0
	global_load_lds_dwordx4 v[2:3], off
	s_mov_b32 m0, s5
	s_cselect_b32 s5, 0, 0
	s_add_i32 s7, s5, s4
	v_lshl_add_u64 v[2:3], v[236:237], 0, s[46:47]
	s_add_i32 s4, s7, 0xa000
	s_mov_b32 s5, m0
	s_mov_b32 m0, s4
	s_nop 0
	global_load_lds_dwordx4 v[2:3], off
	s_mov_b32 m0, s5
	s_mov_b64 s[4:5], 0x60080
	v_lshl_add_u64 v[2:3], v[236:237], 0, s[4:5]
	s_add_i32 s7, s7, 0xc000
	s_mov_b32 s4, m0
	s_mov_b32 m0, s7
	s_nop 0
	global_load_lds_dwordx4 v[2:3], off
	s_mov_b32 m0, s4
	ds_read_b128 v[220:223], v225 offset:8192
	ds_read_b128 v[212:215], v225 offset:8704
	ds_read_b128 v[216:219], v225 offset:10240
	ds_read_b128 v[204:207], v225 offset:10752
	ds_read_b128 v[208:211], v225 offset:12288
	ds_read_b128 v[200:203], v225 offset:12800
	ds_read_b128 v[196:199], v225 offset:14336
	ds_read_b128 v[192:195], v225 offset:14848
	v_sub_f32_e32 v4, v4, v0
	v_sub_f32_e32 v21, v21, v0
	v_sub_f32_e32 v5, v5, v0
	v_sub_f32_e32 v22, v22, v0
	v_sub_f32_e32 v6, v6, v0
	v_sub_f32_e32 v23, v23, v0
	v_sub_f32_e32 v7, v7, v0
	v_sub_f32_e32 v24, v24, v0
	v_sub_f32_e32 v8, v8, v0
	v_sub_f32_e32 v25, v25, v0
	v_sub_f32_e32 v9, v9, v0
	v_sub_f32_e32 v26, v26, v0
	v_sub_f32_e32 v10, v10, v0
	v_sub_f32_e32 v27, v27, v0
	v_sub_f32_e32 v11, v11, v0
	v_sub_f32_e32 v28, v28, v0
	v_sub_f32_e32 v12, v12, v0
	v_sub_f32_e32 v29, v29, v0
	v_sub_f32_e32 v13, v13, v0
	v_sub_f32_e32 v30, v30, v0
	v_sub_f32_e32 v14, v14, v0
	v_sub_f32_e32 v31, v31, v0
	v_sub_f32_e32 v15, v15, v0
	v_sub_f32_e32 v32, v32, v0
	v_sub_f32_e32 v16, v16, v0
	v_sub_f32_e32 v33, v33, v0
	v_sub_f32_e32 v0, v17, v0
	v_exp_f32_e32 v112, v18
	v_exp_f32_e32 v113, v19
	v_exp_f32_e32 v114, v20
	v_exp_f32_e32 v115, v21
	v_exp_f32_e32 v116, v22
	v_exp_f32_e32 v117, v23
	v_exp_f32_e32 v118, v24
	v_exp_f32_e32 v119, v25
	v_exp_f32_e32 v120, v26
	v_exp_f32_e32 v121, v27
	v_exp_f32_e32 v122, v28
	v_exp_f32_e32 v123, v29
	v_exp_f32_e32 v124, v30
	v_exp_f32_e32 v125, v31
	v_exp_f32_e32 v126, v32
	v_exp_f32_e32 v127, v33
	v_exp_f32_e32 v98, v4
	v_exp_f32_e32 v99, v5
	v_exp_f32_e32 v100, v6
	v_exp_f32_e32 v101, v7
	v_exp_f32_e32 v102, v8
	v_exp_f32_e32 v103, v9
	v_exp_f32_e32 v104, v10
	v_exp_f32_e32 v105, v11
	v_exp_f32_e32 v106, v12
	v_exp_f32_e32 v107, v13
	v_exp_f32_e32 v108, v14
	v_exp_f32_e32 v109, v15
	v_exp_f32_e32 v110, v16
	v_exp_f32_e32 v111, v0
	s_waitcnt vmcnt(3) lgkmcnt(0)
	s_barrier
	s_andn2_b64 vcc, exec, s[22:23]
	v_cmp_gt_u32_e64 s[4:5], 32, v253
	s_cbranch_vccnz .LBB0_294
	v_mov_b32_e32 v14, v1
	v_mov_b32_e32 v15, v1
	v_mov_b32_e32 v0, v1
	v_mov_b32_e32 v2, v1
	v_mov_b32_e32 v3, v1
	v_mov_b32_e32 v4, v1
	v_mov_b32_e32 v5, v1
	v_mov_b32_e32 v6, v1
	v_mov_b32_e32 v7, v1
	v_mov_b32_e32 v8, v1
	v_mov_b32_e32 v9, v1
	v_mov_b32_e32 v10, v1
	v_mov_b32_e32 v11, v1
	v_mov_b32_e32 v12, v1
	v_mov_b32_e32 v13, v1
	v_mov_b64_e32 v[78:79], v[14:15]
	v_mov_b64_e32 v[62:63], v[14:15]
	v_mov_b64_e32 v[46:47], v[14:15]
	v_mov_b64_e32 v[30:31], v[14:15]
	s_mov_b32 s72, 0
	s_movk_i32 s76, 0x4000
	s_movk_i32 s78, 0x2000
	v_mov_b32_e32 v231, 0
	s_mov_b32 s77, 6
	s_mov_b64 s[6:7], 0
	v_mov_b64_e32 v[76:77], v[12:13]
	v_mov_b64_e32 v[74:75], v[10:11]
	v_mov_b64_e32 v[72:73], v[8:9]
	v_mov_b64_e32 v[70:71], v[6:7]
	v_mov_b64_e32 v[68:69], v[4:5]
	v_mov_b64_e32 v[66:67], v[2:3]
	v_mov_b64_e32 v[64:65], v[0:1]
	v_mov_b64_e32 v[60:61], v[12:13]
	v_mov_b64_e32 v[58:59], v[10:11]
	v_mov_b64_e32 v[56:57], v[8:9]
	v_mov_b64_e32 v[54:55], v[6:7]
	v_mov_b64_e32 v[52:53], v[4:5]
	v_mov_b64_e32 v[50:51], v[2:3]
	v_mov_b64_e32 v[48:49], v[0:1]
	v_mov_b64_e32 v[44:45], v[12:13]
	v_mov_b64_e32 v[42:43], v[10:11]
	v_mov_b64_e32 v[40:41], v[8:9]
	v_mov_b64_e32 v[38:39], v[6:7]
	v_mov_b64_e32 v[36:37], v[4:5]
	v_mov_b64_e32 v[34:35], v[2:3]
	v_mov_b64_e32 v[32:33], v[0:1]
	v_mov_b64_e32 v[28:29], v[12:13]
	v_mov_b64_e32 v[26:27], v[10:11]
	v_mov_b64_e32 v[24:25], v[8:9]
	v_mov_b64_e32 v[22:23], v[6:7]
	v_mov_b64_e32 v[20:21], v[4:5]
	v_mov_b64_e32 v[18:19], v[2:3]
	v_mov_b64_e32 v[16:17], v[0:1]
	s_cmp_ge_u32 s83, 0x100
	s_cbranch_scc1 .Lstg_280
.LBB0_280:
	s_waitcnt lgkmcnt(7)
	v_mfma_f32_32x32x16_bf16 v[144:159], v[220:223], v[184:187], v[80:95]
	v_add_f32_e32 v2, v112, v113
	v_add_f32_e32 v2, v114, v2
	v_add_f32_e32 v2, v115, v2
	s_lshl_b32 s72, s72, 1
	v_add_f32_e32 v2, v116, v2
	v_add_u32_e32 v0, s72, v245
	v_add_f32_e32 v2, v117, v2
	v_cvt_pk_bf16_f32 v188, v112, v113
	v_cvt_pk_bf16_f32 v189, v114, v115
	s_waitcnt lgkmcnt(6)
	v_mfma_f32_32x32x16_bf16 v[128:143], v[212:215], v[184:187], v[80:95]
	v_add_f32_e32 v2, v118, v2
	v_add_f32_e32 v2, v119, v2
	v_add_f32_e32 v2, v120, v2
	v_add_f32_e32 v2, v121, v2
	v_cvt_pk_bf16_f32 v190, v116, v117
	v_cvt_pk_bf16_f32 v191, v118, v119
	s_waitcnt lgkmcnt(5)
	v_mfma_f32_32x32x16_bf16 v[144:159], v[216:219], v[176:179], v[144:159]
	v_add_f32_e32 v2, v122, v2
	v_add_f32_e32 v2, v123, v2
	v_add_f32_e32 v2, v124, v2
	v_add_f32_e32 v2, v125, v2
	v_cvt_pk_bf16_f32 v180, v120, v121
	v_cvt_pk_bf16_f32 v181, v122, v123
	s_waitcnt lgkmcnt(4)
	v_mfma_f32_32x32x16_bf16 v[128:143], v[204:207], v[176:179], v[128:143]
	v_add_f32_e32 v2, v126, v2
	v_add_f32_e32 v2, v127, v2
	v_add_f32_e32 v2, v96, v2
	v_add_f32_e32 v2, v97, v2
	v_cvt_pk_bf16_f32 v182, v124, v125
	v_cvt_pk_bf16_f32 v183, v126, v127
	s_waitcnt lgkmcnt(3)
	v_mfma_f32_32x32x16_bf16 v[144:159], v[208:211], v[172:175], v[144:159]
	v_add_f32_e32 v2, v98, v2
	v_add_f32_e32 v2, v99, v2
	v_add_f32_e32 v2, v100, v2
	v_add_f32_e32 v2, v101, v2
	v_cvt_pk_bf16_f32 v168, v96, v97
	v_cvt_pk_bf16_f32 v169, v98, v99
	s_waitcnt lgkmcnt(2)
	v_mfma_f32_32x32x16_bf16 v[128:143], v[200:203], v[172:175], v[128:143]
	v_add_f32_e32 v2, v102, v2
	v_add_f32_e32 v2, v103, v2
	v_add_f32_e32 v2, v104, v2
	v_add_f32_e32 v6, v105, v2
	v_cvt_pk_bf16_f32 v170, v100, v101
	v_cvt_pk_bf16_f32 v171, v102, v103
	ds_read_b64_tr_b16 v[2:3], v0 offset:24576
	ds_read_b64_tr_b16 v[4:5], v0 offset:25088
	s_waitcnt lgkmcnt(3)
	v_mfma_f32_32x32x16_bf16 v[144:159], v[196:199], v[164:167], v[144:159]
	v_add_f32_e32 v6, v106, v6
	v_add_f32_e32 v6, v107, v6
	v_add_f32_e32 v6, v108, v6
	v_add_f32_e32 v10, v109, v6
	v_cvt_pk_bf16_f32 v160, v104, v105
	v_cvt_pk_bf16_f32 v161, v106, v107
	ds_read_b64_tr_b16 v[6:7], v0 offset:28672
	ds_read_b64_tr_b16 v[8:9], v0 offset:29184
	s_waitcnt lgkmcnt(4)
	v_mfma_f32_32x32x16_bf16 v[128:143], v[192:195], v[164:167], v[128:143]
	ds_read_b64_tr_b16 v[100:101], v0 offset:32768
	ds_read_b64_tr_b16 v[102:103], v0 offset:33280
	ds_read_b64_tr_b16 v[104:105], v0 offset:36864
	ds_read_b64_tr_b16 v[106:107], v0 offset:37376
	ds_read_b64_tr_b16 v[112:113], v0 offset:25600
	ds_read_b64_tr_b16 v[114:115], v0 offset:26112
	ds_read_b64_tr_b16 v[116:117], v0 offset:29696
	ds_read_b64_tr_b16 v[118:119], v0 offset:30208
	v_add_f32_e32 v10, v110, v10
	v_add_f32_e32 v10, v111, v10
	v_add_f32_e32 v12, 0, v10
	v_cvt_pk_bf16_f32 v162, v108, v109
	v_cvt_pk_bf16_f32 v163, v110, v111
	v_lshl_add_u64 v[14:15], v[234:235], 0, s[6:7]
	v_lshl_add_u64 v[208:209], v[236:237], 0, s[6:7]
	v_lshl_add_u64 v[210:211], v[238:239], 0, s[6:7]
	v_max_f32_e32 v10, v145, v145
	v_max_f32_e32 v11, v144, v144
	v_max_f32_e32 v10, v11, v10
	v_max3_f32 v11, v146, v147, v129
	v_max3_f32 v10, v10, v128, v130
	v_max3_f32 v10, v10, v131, v148
	v_max3_f32 v11, v11, v150, v151
	v_max3_f32 v10, v10, v149, v132
	v_max3_f32 v11, v11, v134, v135
	v_max3_f32 v10, v10, v133, v152
	v_max3_f32 v11, v11, v154, v155
	v_max3_f32 v10, v10, v153, v136
	v_max3_f32 v11, v11, v138, v139
	v_max3_f32 v10, v10, v137, v156
	v_max3_f32 v11, v11, v158, v159
	v_max3_f32 v10, v10, v157, v140
	v_max3_f32 v11, v11, v142, v143
	v_max3_f32 v10, v10, v141, v11
	v_mov_b32_e32 v11, v10
	s_nop 1
	v_permlane32_swap_b32_e32 v10, v11
	v_max_f32_e32 v11, v11, v11
	v_max_f32_e32 v10, v10, v10
	v_max_f32_e32 v10, v10, v11
	v_cmp_lt_f32_e32 vcc, s96, v10
	s_cmp_lg_u64 vcc, 0
	v_add_f32_e32 v212, v231, v12
	s_cselect_b64 s[72:73], -1, 0
	s_cbranch_vccnz .LBB0_288
.LBB0_281:
	s_waitcnt lgkmcnt(10)
	v_mfma_f32_32x32x16_bf16 v[64:79], v[188:191], v[2:5], v[64:79]
	v_exp_f32_e32 v144, v144
	v_exp_f32_e32 v145, v145
	s_waitcnt lgkmcnt(8)
	v_mfma_f32_32x32x16_bf16 v[48:63], v[188:191], v[6:9], v[48:63]
	v_exp_f32_e32 v146, v146
	v_exp_f32_e32 v147, v147
	v_add_u32_e32 v108, s76, v225
	ds_read_b128 v[96:99], v108
	ds_read_b128 v[10:13], v108 offset:512
	s_waitcnt lgkmcnt(8)
	v_mfma_f32_32x32x16_bf16 v[32:47], v[188:191], v[100:103], v[32:47]
	v_exp_f32_e32 v148, v148
	v_exp_f32_e32 v149, v149
	ds_read_b64_tr_b16 v[100:101], v0 offset:33792
	ds_read_b64_tr_b16 v[102:103], v0 offset:34304
	s_waitcnt lgkmcnt(8)
	v_mfma_f32_32x32x16_bf16 v[16:31], v[188:191], v[104:107], v[16:31]
	v_exp_f32_e32 v150, v150
	v_exp_f32_e32 v151, v151
	ds_read_b128 v[204:207], v108 offset:2048
	ds_read_b128 v[192:195], v108 offset:2560
	ds_read_b64_tr_b16 v[104:105], v0 offset:37888
	ds_read_b64_tr_b16 v[106:107], v0 offset:38400
	s_waitcnt lgkmcnt(10)
	v_mfma_f32_32x32x16_bf16 v[64:79], v[180:183], v[112:115], v[64:79]
	v_exp_f32_e32 v152, v152
	v_exp_f32_e32 v153, v153
	ds_read_b64_tr_b16 v[112:113], v0 offset:26624
	ds_read_b64_tr_b16 v[114:115], v0 offset:27136
	s_waitcnt lgkmcnt(10)
	v_mfma_f32_32x32x16_bf16 v[48:63], v[180:183], v[116:119], v[48:63]
	v_exp_f32_e32 v154, v154
	v_exp_f32_e32 v155, v155
	ds_read_b128 v[200:203], v108 offset:4096
	ds_read_b128 v[6:9], v108 offset:4608
	ds_read_b64_tr_b16 v[116:117], v0 offset:30720
	ds_read_b64_tr_b16 v[118:119], v0 offset:31232
	s_waitcnt lgkmcnt(10)
	v_mfma_f32_32x32x16_bf16 v[32:47], v[180:183], v[100:103], v[32:47]
	v_exp_f32_e32 v156, v156
	v_exp_f32_e32 v157, v157
	ds_read_b64_tr_b16 v[100:101], v0 offset:34816
	ds_read_b64_tr_b16 v[102:103], v0 offset:35328
	s_waitcnt lgkmcnt(8)
; #define WAIT_BAR(N) asm volatile("s_waitcnt vmcnt(" #N ") lgkmcnt(0)\n\ts_barrier":::"memory")
;   #define RESC() do{ if(resc){ asm volatile("s_waitcnt lgkmcnt(0)":::"memory"); \
;       _Pragma("unroll") for(int d_=0;d_<2;++d_) _Pragma("unroll") for(int r=0;r<16;++r)o[d_][r]*=wsf[crow(r,hi)]; } }while(0)
;   #define ROT() do{sl_prev=sl_cur;sl_cur=sl_next;sl_next=(sl_next==(NSLOT-1)*SLOTB)?0:sl_next+SLOTB;}while(0)
; #define WAIT_BAR(N) asm volatile("s_waitcnt vmcnt(" #N ") lgkmcnt(0)\n\ts_barrier":::"memory")
;   #define RESC() do{ if(resc){ asm volatile("s_waitcnt lgkmcnt(0)":::"memory"); \
;       _Pragma("unroll") for(int d_=0;d_<4;++d_) _Pragma("unroll") for(int r=0;r<16;++r)o[d_][r]*=wsf[crow(r,hi)]; } }while(0)
;   #define ROT() do{sl_prev=sl_cur;sl_cur=sl_next;sl_next=(sl_next==(NSLOT-1)*SLOTB)?0:sl_next+SLOTB;}while(0)
; template<int THRL,bool BIAS> __device__ __forceinline__ void attn_unit(int b,int qb,const bf16*Q,const bf16*__restrict__ K,const bf16*__restrict__ V,bf16*O,const float*__restrict__ biasg,char*shm,const int tid_in,const bool comb,const bf16*O0,const float lam,const float osc,const float*__restrict__ ...
;     ...
;   int t=1;
;     ...
;   for(;t+5<NT;t+=2){
;     STEP(pB0,pB1,pA0,pA1,t,true,true,true);     WAIT_BAR(3); RESC(); ROT();
;     STEP(pA0,pA1,pB0,pB1,t+1,true,true,true);   WAIT_BAR(3); RESC(); ROT();
	v_mfma_f32_32x32x16_bf16 v[16:31], v[180:183], v[104:107], v[16:31]
	v_exp_f32_e32 v158, v158
	v_exp_f32_e32 v159, v159
	ds_read_b128 v[196:199], v108 offset:6144
	ds_read_b128 v[2:5], v108 offset:6656
	ds_read_b64_tr_b16 v[104:105], v0 offset:38912
	ds_read_b64_tr_b16 v[106:107], v0 offset:39424
	s_waitcnt lgkmcnt(10)
	v_mfma_f32_32x32x16_bf16 v[64:79], v[168:171], v[112:115], v[64:79]
	v_exp_f32_e32 v128, v128
	v_exp_f32_e32 v129, v129
	ds_read_b64_tr_b16 v[112:113], v0 offset:27648
	ds_read_b64_tr_b16 v[114:115], v0 offset:28160
	s_waitcnt lgkmcnt(8)
	v_mfma_f32_32x32x16_bf16 v[48:63], v[168:171], v[116:119], v[48:63]
	v_exp_f32_e32 v130, v130
	v_exp_f32_e32 v131, v131
	ds_read_b64_tr_b16 v[116:117], v0 offset:31744
	ds_read_b64_tr_b16 v[118:119], v0 offset:32256
	s_waitcnt lgkmcnt(8)
	v_mfma_f32_32x32x16_bf16 v[32:47], v[168:171], v[100:103], v[32:47]
	v_exp_f32_e32 v132, v132
	v_exp_f32_e32 v133, v133
	ds_read_b64_tr_b16 v[100:101], v0 offset:35840
	ds_read_b64_tr_b16 v[102:103], v0 offset:36352
	s_waitcnt lgkmcnt(6)
	v_mfma_f32_32x32x16_bf16 v[16:31], v[168:171], v[104:107], v[16:31]
	v_exp_f32_e32 v134, v134
	v_exp_f32_e32 v135, v135
	ds_read_b64_tr_b16 v[104:105], v0 offset:39936
	ds_read_b64_tr_b16 v[106:107], v0 offset:40448
	s_waitcnt lgkmcnt(6)
	v_mfma_f32_32x32x16_bf16 v[64:79], v[160:163], v[112:115], v[64:79]
	v_exp_f32_e32 v136, v136
	v_exp_f32_e32 v137, v137
	s_waitcnt lgkmcnt(4)
	v_mfma_f32_32x32x16_bf16 v[48:63], v[160:163], v[116:119], v[48:63]
	v_exp_f32_e32 v138, v138
	v_exp_f32_e32 v139, v139
	s_waitcnt lgkmcnt(2)
	v_mfma_f32_32x32x16_bf16 v[32:47], v[160:163], v[100:103], v[32:47]
	v_exp_f32_e32 v140, v140
	v_exp_f32_e32 v141, v141
	s_waitcnt lgkmcnt(0)
	v_mfma_f32_32x32x16_bf16 v[16:31], v[160:163], v[104:107], v[16:31]
	v_exp_f32_e32 v142, v142
	v_exp_f32_e32 v143, v143
	s_waitcnt vmcnt(0) lgkmcnt(0)
	s_barrier
	s_andn2_b64 vcc, exec, s[72:73]
	v_add_u32_e32 v0, s62, v230
	s_cbranch_vccnz .LBB0_283
	s_waitcnt lgkmcnt(0)
	ds_read_b128 v[100:103], v0 offset:96
	ds_read_b128 v[104:107], v0 offset:64
	ds_read_b128 v[108:111], v0 offset:32
	ds_read_b128 v[112:115], v0
	s_waitcnt lgkmcnt(3)
	v_pk_mul_f32 v[76:77], v[76:77], v[100:101]
	s_waitcnt lgkmcnt(2)
	v_pk_mul_f32 v[72:73], v[72:73], v[104:105]
	s_waitcnt lgkmcnt(1)
	v_pk_mul_f32 v[68:69], v[68:69], v[108:109]
	v_pk_mul_f32 v[78:79], v[78:79], v[102:103]
	v_pk_mul_f32 v[74:75], v[74:75], v[106:107]
	v_pk_mul_f32 v[70:71], v[70:71], v[110:111]
	s_waitcnt lgkmcnt(0)
	v_pk_mul_f32 v[66:67], v[66:67], v[114:115]
	v_pk_mul_f32 v[64:65], v[64:65], v[112:113]
	v_pk_mul_f32 v[60:61], v[60:61], v[100:101]
	v_pk_mul_f32 v[56:57], v[56:57], v[104:105]
	v_pk_mul_f32 v[52:53], v[52:53], v[108:109]
	v_pk_mul_f32 v[62:63], v[62:63], v[102:103]
	v_pk_mul_f32 v[58:59], v[58:59], v[106:107]
	v_pk_mul_f32 v[54:55], v[54:55], v[110:111]
	v_pk_mul_f32 v[50:51], v[50:51], v[114:115]
	v_pk_mul_f32 v[48:49], v[48:49], v[112:113]
	v_pk_mul_f32 v[44:45], v[44:45], v[100:101]
	v_pk_mul_f32 v[40:41], v[40:41], v[104:105]
	v_pk_mul_f32 v[36:37], v[36:37], v[108:109]
	v_pk_mul_f32 v[46:47], v[46:47], v[102:103]
	v_pk_mul_f32 v[42:43], v[42:43], v[106:107]
	v_pk_mul_f32 v[38:39], v[38:39], v[110:111]
	v_pk_mul_f32 v[34:35], v[34:35], v[114:115]
	v_pk_mul_f32 v[32:33], v[32:33], v[112:113]
	v_pk_mul_f32 v[28:29], v[28:29], v[100:101]
	v_pk_mul_f32 v[24:25], v[24:25], v[104:105]
	v_pk_mul_f32 v[20:21], v[20:21], v[108:109]
	v_pk_mul_f32 v[30:31], v[30:31], v[102:103]
	v_pk_mul_f32 v[26:27], v[26:27], v[106:107]
	v_pk_mul_f32 v[22:23], v[22:23], v[110:111]
	v_pk_mul_f32 v[18:19], v[18:19], v[114:115]
	v_pk_mul_f32 v[16:17], v[16:17], v[112:113]
.LBB0_283:
	v_lshl_add_u64 v[100:101], v[14:15], 0, s[56:57]
	s_add_i32 s72, s78, s64
	s_mov_b32 s73, m0
	s_mov_b32 m0, s72
	s_nop 0
	global_load_lds_dwordx4 v[100:101], off
	s_mov_b32 m0, s73
	v_lshl_add_u64 v[100:101], v[208:209], 0, s[48:49]
	s_lshl_b32 s72, s76, 1
	s_add_i32 s72, s72, s63
	s_mov_b32 s73, m0
	s_mov_b32 m0, s72
	s_nop 0
	global_load_lds_dwordx4 v[100:101], off
	s_mov_b32 m0, s73
	v_lshl_add_u64 v[100:101], v[210:211], 0, s[48:49]
	s_addk_i32 s72, 0x2000
	s_mov_b32 s73, m0
	s_mov_b32 m0, s72
	s_nop 0
	global_load_lds_dwordx4 v[100:101], off
	s_mov_b32 m0, s73
	s_add_i32 s72, s76, 0x2000
	s_cmpk_lg_i32 s76, 0x4000
	s_cselect_b32 s87, s72, 0
	v_mfma_f32_32x32x16_bf16 v[112:127], v[96:99], v[184:187], v[80:95]
	v_add_f32_e32 v100, v144, v145
	v_add_f32_e32 v100, v146, v100
	v_add_f32_e32 v100, v147, v100
	s_lshl_b32 s72, s78, 1
	v_add_f32_e32 v100, v148, v100
	v_add_u32_e32 v233, s72, v245
	v_add_f32_e32 v96, v149, v100
	v_cvt_pk_bf16_f32 v188, v144, v145
	v_cvt_pk_bf16_f32 v189, v146, v147
	s_nop 0
	v_add_f32_e32 v96, v150, v96
	v_add_f32_e32 v96, v151, v96
	v_add_f32_e32 v96, v152, v96
	v_add_f32_e32 v144, v153, v96
	v_mfma_f32_32x32x16_bf16 v[96:111], v[10:13], v[184:187], v[80:95]
	v_cvt_pk_bf16_f32 v190, v148, v149
	v_cvt_pk_bf16_f32 v191, v150, v151
	v_mfma_f32_32x32x16_bf16 v[112:127], v[204:207], v[176:179], v[112:127]
	v_add_f32_e32 v10, v154, v144
	v_add_f32_e32 v10, v155, v10
	v_add_f32_e32 v10, v156, v10
	v_add_f32_e32 v10, v157, v10
	v_cvt_pk_bf16_f32 v180, v152, v153
	v_cvt_pk_bf16_f32 v181, v154, v155
	v_mfma_f32_32x32x16_bf16 v[96:111], v[192:195], v[176:179], v[96:111]
	v_add_f32_e32 v10, v158, v10
	v_add_f32_e32 v10, v159, v10
	v_add_f32_e32 v10, v128, v10
	v_add_f32_e32 v10, v129, v10
	v_cvt_pk_bf16_f32 v182, v156, v157
	v_cvt_pk_bf16_f32 v183, v158, v159
	v_mfma_f32_32x32x16_bf16 v[112:127], v[200:203], v[172:175], v[112:127]
	v_add_f32_e32 v10, v130, v10
	v_add_f32_e32 v10, v131, v10
	v_add_f32_e32 v10, v132, v10
	v_add_f32_e32 v10, v133, v10
	v_cvt_pk_bf16_f32 v168, v128, v129
	v_cvt_pk_bf16_f32 v169, v130, v131
	v_mfma_f32_32x32x16_bf16 v[96:111], v[6:9], v[172:175], v[96:111]
	v_add_f32_e32 v6, v134, v10
	v_add_f32_e32 v6, v135, v6
	v_add_f32_e32 v6, v136, v6
	v_add_f32_e32 v10, v137, v6
	v_cvt_pk_bf16_f32 v170, v132, v133
	v_cvt_pk_bf16_f32 v171, v134, v135
	ds_read_b64_tr_b16 v[6:7], v233 offset:24576
	ds_read_b64_tr_b16 v[8:9], v233 offset:25088
	v_mfma_f32_32x32x16_bf16 v[112:127], v[196:199], v[164:167], v[112:127]
	v_add_f32_e32 v10, v138, v10
	v_add_f32_e32 v10, v139, v10
	v_add_f32_e32 v10, v140, v10
	v_add_f32_e32 v128, v141, v10
	v_cvt_pk_bf16_f32 v160, v136, v137
	v_cvt_pk_bf16_f32 v161, v138, v139
	ds_read_b64_tr_b16 v[10:11], v233 offset:28672
	ds_read_b64_tr_b16 v[12:13], v233 offset:29184
	v_mfma_f32_32x32x16_bf16 v[96:111], v[2:5], v[164:167], v[96:111]
	ds_read_b64_tr_b16 v[144:145], v233 offset:32768
	ds_read_b64_tr_b16 v[146:147], v233 offset:33280
	ds_read_b64_tr_b16 v[148:149], v233 offset:36864
	ds_read_b64_tr_b16 v[150:151], v233 offset:37376
	ds_read_b64_tr_b16 v[152:153], v233 offset:25600
	ds_read_b64_tr_b16 v[154:155], v233 offset:26112
	ds_read_b64_tr_b16 v[156:157], v233 offset:29696
	ds_read_b64_tr_b16 v[158:159], v233 offset:30208
	v_add_f32_e32 v2, v142, v128
	v_add_f32_e32 v2, v143, v2
	v_add_f32_e32 v4, 0, v2
	v_cvt_pk_bf16_f32 v162, v140, v141
	v_cvt_pk_bf16_f32 v163, v142, v143
	v_max_f32_e32 v2, v113, v113
	v_max_f32_e32 v3, v112, v112
	v_max_f32_e32 v2, v3, v2
	v_max3_f32 v3, v114, v115, v97
	v_max3_f32 v2, v2, v96, v98
	v_max3_f32 v2, v2, v99, v116
	v_max3_f32 v3, v3, v118, v119
	v_max3_f32 v2, v2, v117, v100
	v_max3_f32 v3, v3, v102, v103
	v_max3_f32 v2, v2, v101, v120
	v_max3_f32 v3, v3, v122, v123
	v_max3_f32 v2, v2, v121, v104
	v_max3_f32 v3, v3, v106, v107
	v_max3_f32 v2, v2, v105, v124
	v_max3_f32 v3, v3, v126, v127
	v_max3_f32 v2, v2, v125, v108
	v_max3_f32 v3, v3, v110, v111
	v_max3_f32 v2, v2, v109, v3
	v_mov_b32_e32 v3, v2
	s_nop 1
	v_permlane32_swap_b32_e32 v2, v3
	v_max_f32_e32 v3, v3, v3
	v_max_f32_e32 v2, v2, v2
	v_max_f32_e32 v2, v2, v3
	v_cmp_lt_f32_e32 vcc, s96, v2
	s_cmp_lg_u64 vcc, 0
	v_add_f32_e32 v231, v212, v4
	s_cselect_b64 s[72:73], -1, 0
	s_cbranch_vccnz .LBB0_291
; #define WAIT_BAR(N) asm volatile("s_waitcnt vmcnt(" #N ") lgkmcnt(0)\n\ts_barrier":::"memory")
;   #define RESC() do{ if(resc){ asm volatile("s_waitcnt lgkmcnt(0)":::"memory"); \
;       _Pragma("unroll") for(int d_=0;d_<2;++d_) _Pragma("unroll") for(int r=0;r<16;++r)o[d_][r]*=wsf[crow(r,hi)]; } }while(0)
;   #define ROT() do{sl_prev=sl_cur;sl_cur=sl_next;sl_next=(sl_next==(NSLOT-1)*SLOTB)?0:sl_next+SLOTB;}while(0)
; #define WAIT_BAR(N) asm volatile("s_waitcnt vmcnt(" #N ") lgkmcnt(0)\n\ts_barrier":::"memory")
;   #define RESC() do{ if(resc){ asm volatile("s_waitcnt lgkmcnt(0)":::"memory"); \
;       _Pragma("unroll") for(int d_=0;d_<4;++d_) _Pragma("unroll") for(int r=0;r<16;++r)o[d_][r]*=wsf[crow(r,hi)]; } }while(0)
;   #define ROT() do{sl_prev=sl_cur;sl_cur=sl_next;sl_next=(sl_next==(NSLOT-1)*SLOTB)?0:sl_next+SLOTB;}while(0)
; template<int THRL,bool BIAS> __device__ __forceinline__ void attn_unit(int b,int qb,const bf16*Q,const bf16*__restrict__ K,const bf16*__restrict__ V,bf16*O,const float*__restrict__ biasg,char*shm,const int tid_in,const bool comb,const bf16*O0,const float lam,const float osc,const float*__restrict__ ...
;     ...
;   int t=1;
;     ...
;   for(;t+5<NT;t+=2){
;     STEP(pB0,pB1,pA0,pA1,t,true,true,true);     WAIT_BAR(3); RESC(); ROT();
;     STEP(pA0,pA1,pB0,pB1,t+1,true,true,true);   WAIT_BAR(3); RESC(); ROT();
;   }
.LBB0_284:
	s_waitcnt lgkmcnt(10)
	v_mfma_f32_32x32x16_bf16 v[64:79], v[188:191], v[6:9], v[64:79]
	v_exp_f32_e32 v112, v112
	v_exp_f32_e32 v113, v113
	s_waitcnt lgkmcnt(8)
	v_mfma_f32_32x32x16_bf16 v[48:63], v[188:191], v[10:13], v[48:63]
	v_exp_f32_e32 v114, v114
	v_exp_f32_e32 v115, v115
	v_add_u32_e32 v10, s87, v225
	ds_read_b128 v[220:223], v10
	ds_read_b128 v[212:215], v10 offset:512
	s_waitcnt lgkmcnt(8)
	v_mfma_f32_32x32x16_bf16 v[32:47], v[188:191], v[144:147], v[32:47]
	v_exp_f32_e32 v116, v116
	v_exp_f32_e32 v117, v117
	ds_read_b64_tr_b16 v[144:145], v233 offset:33792
	ds_read_b64_tr_b16 v[146:147], v233 offset:34304
	s_waitcnt lgkmcnt(8)
	v_mfma_f32_32x32x16_bf16 v[16:31], v[188:191], v[148:151], v[16:31]
	v_exp_f32_e32 v118, v118
	v_exp_f32_e32 v119, v119
	ds_read_b128 v[216:219], v10 offset:2048
	ds_read_b128 v[204:207], v10 offset:2560
	ds_read_b64_tr_b16 v[148:149], v233 offset:37888
	ds_read_b64_tr_b16 v[150:151], v233 offset:38400
	s_waitcnt lgkmcnt(10)
	v_mfma_f32_32x32x16_bf16 v[64:79], v[180:183], v[152:155], v[64:79]
	v_exp_f32_e32 v120, v120
	v_exp_f32_e32 v121, v121
	ds_read_b64_tr_b16 v[152:153], v233 offset:26624
	ds_read_b64_tr_b16 v[154:155], v233 offset:27136
	s_waitcnt lgkmcnt(10)
	v_mfma_f32_32x32x16_bf16 v[48:63], v[180:183], v[156:159], v[48:63]
	v_exp_f32_e32 v122, v122
	v_exp_f32_e32 v123, v123
	ds_read_b128 v[208:211], v10 offset:4096
	ds_read_b128 v[200:203], v10 offset:4608
	ds_read_b64_tr_b16 v[156:157], v233 offset:30720
	ds_read_b64_tr_b16 v[158:159], v233 offset:31232
	s_waitcnt lgkmcnt(10)
	v_mfma_f32_32x32x16_bf16 v[32:47], v[180:183], v[144:147], v[32:47]
	v_exp_f32_e32 v124, v124
	v_exp_f32_e32 v125, v125
	ds_read_b64_tr_b16 v[144:145], v233 offset:34816
	ds_read_b64_tr_b16 v[146:147], v233 offset:35328
	s_waitcnt lgkmcnt(8)
	v_mfma_f32_32x32x16_bf16 v[16:31], v[180:183], v[148:151], v[16:31]
	v_exp_f32_e32 v126, v126
	v_exp_f32_e32 v127, v127
	ds_read_b128 v[196:199], v10 offset:6144
	ds_read_b128 v[192:195], v10 offset:6656
	ds_read_b64_tr_b16 v[148:149], v233 offset:38912
	ds_read_b64_tr_b16 v[150:151], v233 offset:39424
	s_waitcnt lgkmcnt(10)
	v_mfma_f32_32x32x16_bf16 v[64:79], v[168:171], v[152:155], v[64:79]
	v_exp_f32_e32 v96, v96
	v_exp_f32_e32 v97, v97
	ds_read_b64_tr_b16 v[152:153], v233 offset:27648
	ds_read_b64_tr_b16 v[154:155], v233 offset:28160
	s_waitcnt lgkmcnt(8)
	v_mfma_f32_32x32x16_bf16 v[48:63], v[168:171], v[156:159], v[48:63]
	v_exp_f32_e32 v98, v98
	v_exp_f32_e32 v99, v99
	ds_read_b64_tr_b16 v[156:157], v233 offset:31744
	ds_read_b64_tr_b16 v[158:159], v233 offset:32256
	s_waitcnt lgkmcnt(8)
	v_mfma_f32_32x32x16_bf16 v[32:47], v[168:171], v[144:147], v[32:47]
	v_exp_f32_e32 v100, v100
	v_exp_f32_e32 v101, v101
	ds_read_b64_tr_b16 v[144:145], v233 offset:35840
	ds_read_b64_tr_b16 v[146:147], v233 offset:36352
	s_waitcnt lgkmcnt(6)
	v_mfma_f32_32x32x16_bf16 v[16:31], v[168:171], v[148:151], v[16:31]
	v_exp_f32_e32 v102, v102
	v_exp_f32_e32 v103, v103
	ds_read_b64_tr_b16 v[148:149], v233 offset:39936
	ds_read_b64_tr_b16 v[150:151], v233 offset:40448
	s_waitcnt lgkmcnt(6)
	v_mfma_f32_32x32x16_bf16 v[64:79], v[160:163], v[152:155], v[64:79]
	v_exp_f32_e32 v104, v104
	v_exp_f32_e32 v105, v105
	s_waitcnt lgkmcnt(4)
	v_mfma_f32_32x32x16_bf16 v[48:63], v[160:163], v[156:159], v[48:63]
	v_exp_f32_e32 v106, v106
	v_exp_f32_e32 v107, v107
	s_waitcnt lgkmcnt(2)
	v_mfma_f32_32x32x16_bf16 v[32:47], v[160:163], v[144:147], v[32:47]
	v_exp_f32_e32 v108, v108
	v_exp_f32_e32 v109, v109
	s_waitcnt lgkmcnt(0)
	v_mfma_f32_32x32x16_bf16 v[16:31], v[160:163], v[148:151], v[16:31]
	v_exp_f32_e32 v110, v110
	v_exp_f32_e32 v111, v111
	s_waitcnt vmcnt(0) lgkmcnt(0)
	s_barrier
	s_andn2_b64 vcc, exec, s[72:73]
	s_cbranch_vccnz .LBB0_286
	s_waitcnt lgkmcnt(0)
	ds_read_b128 v[2:5], v0 offset:96
	ds_read_b128 v[6:9], v0 offset:64
	ds_read_b128 v[10:13], v0 offset:32
	ds_read_b128 v[128:131], v0
	s_waitcnt lgkmcnt(3)
	v_pk_mul_f32 v[76:77], v[76:77], v[2:3]
	s_waitcnt lgkmcnt(2)
	v_pk_mul_f32 v[72:73], v[72:73], v[6:7]
	s_waitcnt lgkmcnt(1)
	v_pk_mul_f32 v[68:69], v[68:69], v[10:11]
	v_pk_mul_f32 v[78:79], v[78:79], v[4:5]
	v_pk_mul_f32 v[74:75], v[74:75], v[8:9]
	v_pk_mul_f32 v[70:71], v[70:71], v[12:13]
	s_waitcnt lgkmcnt(0)
	v_pk_mul_f32 v[66:67], v[66:67], v[130:131]
	v_pk_mul_f32 v[64:65], v[64:65], v[128:129]
	v_pk_mul_f32 v[60:61], v[60:61], v[2:3]
	v_pk_mul_f32 v[56:57], v[56:57], v[6:7]
	v_pk_mul_f32 v[52:53], v[52:53], v[10:11]
	v_pk_mul_f32 v[62:63], v[62:63], v[4:5]
	v_pk_mul_f32 v[58:59], v[58:59], v[8:9]
	v_pk_mul_f32 v[54:55], v[54:55], v[12:13]
	v_pk_mul_f32 v[50:51], v[50:51], v[130:131]
	v_pk_mul_f32 v[48:49], v[48:49], v[128:129]
	v_pk_mul_f32 v[44:45], v[44:45], v[2:3]
	v_pk_mul_f32 v[40:41], v[40:41], v[6:7]
	v_pk_mul_f32 v[36:37], v[36:37], v[10:11]
	v_pk_mul_f32 v[46:47], v[46:47], v[4:5]
	v_pk_mul_f32 v[42:43], v[42:43], v[8:9]
	v_pk_mul_f32 v[38:39], v[38:39], v[12:13]
	v_pk_mul_f32 v[34:35], v[34:35], v[130:131]
	v_pk_mul_f32 v[32:33], v[32:33], v[128:129]
	v_pk_mul_f32 v[28:29], v[28:29], v[2:3]
	v_pk_mul_f32 v[24:25], v[24:25], v[6:7]
	v_pk_mul_f32 v[20:21], v[20:21], v[10:11]
	v_pk_mul_f32 v[30:31], v[30:31], v[4:5]
	v_pk_mul_f32 v[26:27], v[26:27], v[8:9]
	v_pk_mul_f32 v[22:23], v[22:23], v[12:13]
	v_pk_mul_f32 v[18:19], v[18:19], v[130:131]
	v_pk_mul_f32 v[16:17], v[16:17], v[128:129]
.LBB0_286:
	v_lshl_add_u64 v[2:3], v[234:235], 0, s[6:7]
	v_lshl_add_u64 v[2:3], v[2:3], 0, s[52:53]
	s_add_i32 s72, s76, s64
	s_mov_b32 s73, m0
	s_mov_b32 m0, s72
	s_nop 0
	global_load_lds_dwordx4 v[2:3], off
	s_mov_b32 m0, s73
	v_lshl_add_u64 v[2:3], v[236:237], 0, s[6:7]
	v_lshl_add_u64 v[2:3], v[2:3], 0, s[50:51]
	s_lshl_b32 s72, s87, 1
	s_add_i32 s72, s72, s63
	s_mov_b32 s73, m0
	s_mov_b32 m0, s72
	s_nop 0
	global_load_lds_dwordx4 v[2:3], off
	s_mov_b32 m0, s73
	v_lshl_add_u64 v[2:3], v[238:239], 0, s[6:7]
	v_lshl_add_u64 v[2:3], v[2:3], 0, s[50:51]
	s_addk_i32 s72, 0x2000
	s_mov_b32 s73, m0
	s_mov_b32 m0, s72
	s_nop 0
	global_load_lds_dwordx4 v[2:3], off
	s_mov_b32 m0, s73
	s_add_i32 s72, s87, 0x2000
	s_cmpk_lg_i32 s87, 0x4000
	s_cselect_b32 s88, s72, 0
	s_add_i32 s72, s77, 2
	s_add_u32 s6, s6, 0xc0000
	s_addc_u32 s7, s7, 0
	s_cmp_ge_u32 s72, s60
	s_cbranch_scc1 .Lstg_exit_lead
	s_mov_b32 s77, s72
	s_mov_b32 s72, s76
	s_mov_b32 s78, s87
	s_mov_b32 s76, s88
	s_branch .LBB0_280

.Lstg_281:
	s_waitcnt vmcnt(0)
	s_barrier
	v_lshl_add_u64 v[10:11], v[14:15], 0, s[56:57]
	s_add_i32 vcc_lo, s78, s64
	s_mov_b32 vcc_hi, m0
	s_mov_b32 m0, vcc_lo
	s_nop 0
	global_load_lds_dwordx4 v[10:11], off
	s_mov_b32 m0, vcc_hi
	v_lshl_add_u64 v[10:11], v[208:209], 0, s[48:49]
	s_lshl_b32 vcc_lo, s76, 1
	s_add_i32 vcc_lo, vcc_lo, s63
	s_mov_b32 vcc_hi, m0
	s_mov_b32 m0, vcc_lo
	s_nop 0
	global_load_lds_dwordx4 v[10:11], off
	s_mov_b32 m0, vcc_hi
	v_lshl_add_u64 v[10:11], v[210:211], 0, s[48:49]
	s_addk_i32 vcc_lo, 0x2000
	s_mov_b32 vcc_hi, m0
	s_mov_b32 m0, vcc_lo
	s_nop 0
	global_load_lds_dwordx4 v[10:11], off
	s_mov_b32 m0, vcc_hi
	s_waitcnt lgkmcnt(10)
	v_mfma_f32_32x32x16_bf16 v[64:79], v[188:191], v[2:5], v[64:79]
	v_exp_f32_e32 v144, v144
	v_exp_f32_e32 v145, v145
	s_waitcnt lgkmcnt(8)
	v_mfma_f32_32x32x16_bf16 v[48:63], v[188:191], v[6:9], v[48:63]
	v_exp_f32_e32 v146, v146
	v_exp_f32_e32 v147, v147
	v_add_u32_e32 v108, s76, v225
	ds_read_b128 v[96:99], v108
	ds_read_b128 v[10:13], v108 offset:512
	s_waitcnt lgkmcnt(8)
	v_mfma_f32_32x32x16_bf16 v[32:47], v[188:191], v[100:103], v[32:47]
	v_exp_f32_e32 v148, v148
	v_exp_f32_e32 v149, v149
	ds_read_b64_tr_b16 v[100:101], v0 offset:33792
	ds_read_b64_tr_b16 v[102:103], v0 offset:34304
	s_waitcnt lgkmcnt(8)
	v_mfma_f32_32x32x16_bf16 v[16:31], v[188:191], v[104:107], v[16:31]
	v_exp_f32_e32 v150, v150
	v_exp_f32_e32 v151, v151
	ds_read_b128 v[204:207], v108 offset:2048
	ds_read_b128 v[192:195], v108 offset:2560
	ds_read_b64_tr_b16 v[104:105], v0 offset:37888
	ds_read_b64_tr_b16 v[106:107], v0 offset:38400
	s_waitcnt lgkmcnt(10)
	v_mfma_f32_32x32x16_bf16 v[64:79], v[180:183], v[112:115], v[64:79]
	v_exp_f32_e32 v152, v152
	v_exp_f32_e32 v153, v153
	ds_read_b64_tr_b16 v[112:113], v0 offset:26624
	ds_read_b64_tr_b16 v[114:115], v0 offset:27136
	s_waitcnt lgkmcnt(10)
	v_mfma_f32_32x32x16_bf16 v[48:63], v[180:183], v[116:119], v[48:63]
	v_exp_f32_e32 v154, v154
	v_exp_f32_e32 v155, v155
	ds_read_b128 v[200:203], v108 offset:4096
	ds_read_b128 v[6:9], v108 offset:4608
	ds_read_b64_tr_b16 v[116:117], v0 offset:30720
	ds_read_b64_tr_b16 v[118:119], v0 offset:31232
	s_waitcnt lgkmcnt(10)
	v_mfma_f32_32x32x16_bf16 v[32:47], v[180:183], v[100:103], v[32:47]
	v_exp_f32_e32 v156, v156
	v_exp_f32_e32 v157, v157
	ds_read_b64_tr_b16 v[100:101], v0 offset:34816
	ds_read_b64_tr_b16 v[102:103], v0 offset:35328
	s_waitcnt lgkmcnt(8)
	v_mfma_f32_32x32x16_bf16 v[16:31], v[180:183], v[104:107], v[16:31]
	v_exp_f32_e32 v158, v158
	v_exp_f32_e32 v159, v159
	ds_read_b128 v[196:199], v108 offset:6144
	ds_read_b128 v[2:5], v108 offset:6656
	ds_read_b64_tr_b16 v[104:105], v0 offset:38912
	ds_read_b64_tr_b16 v[106:107], v0 offset:39424
	s_waitcnt lgkmcnt(10)
	v_mfma_f32_32x32x16_bf16 v[64:79], v[168:171], v[112:115], v[64:79]
	v_exp_f32_e32 v128, v128
	v_exp_f32_e32 v129, v129
	ds_read_b64_tr_b16 v[112:113], v0 offset:27648
	ds_read_b64_tr_b16 v[114:115], v0 offset:28160
	s_waitcnt lgkmcnt(8)
	v_mfma_f32_32x32x16_bf16 v[48:63], v[168:171], v[116:119], v[48:63]
	v_exp_f32_e32 v130, v130
	v_exp_f32_e32 v131, v131
	ds_read_b64_tr_b16 v[116:117], v0 offset:31744
	ds_read_b64_tr_b16 v[118:119], v0 offset:32256
	s_waitcnt lgkmcnt(8)
	v_mfma_f32_32x32x16_bf16 v[32:47], v[168:171], v[100:103], v[32:47]
	v_exp_f32_e32 v132, v132
	v_exp_f32_e32 v133, v133
	ds_read_b64_tr_b16 v[100:101], v0 offset:35840
	ds_read_b64_tr_b16 v[102:103], v0 offset:36352
	s_waitcnt lgkmcnt(6)
	v_mfma_f32_32x32x16_bf16 v[16:31], v[168:171], v[104:107], v[16:31]
	v_exp_f32_e32 v134, v134
	v_exp_f32_e32 v135, v135
	ds_read_b64_tr_b16 v[104:105], v0 offset:39936
	ds_read_b64_tr_b16 v[106:107], v0 offset:40448
	s_waitcnt lgkmcnt(6)
	v_mfma_f32_32x32x16_bf16 v[64:79], v[160:163], v[112:115], v[64:79]
	v_exp_f32_e32 v136, v136
	v_exp_f32_e32 v137, v137
	s_waitcnt lgkmcnt(4)
	v_mfma_f32_32x32x16_bf16 v[48:63], v[160:163], v[116:119], v[48:63]
	v_exp_f32_e32 v138, v138
	v_exp_f32_e32 v139, v139
	s_waitcnt lgkmcnt(2)
	v_mfma_f32_32x32x16_bf16 v[32:47], v[160:163], v[100:103], v[32:47]
	v_exp_f32_e32 v140, v140
	v_exp_f32_e32 v141, v141
	s_waitcnt lgkmcnt(0)
	v_mfma_f32_32x32x16_bf16 v[16:31], v[160:163], v[104:107], v[16:31]
	v_exp_f32_e32 v142, v142
	v_exp_f32_e32 v143, v143
	s_waitcnt lgkmcnt(0)
	s_andn2_b64 vcc, exec, s[72:73]
	v_add_u32_e32 v0, s62, v230
	s_cbranch_vccnz .Lstg_283

	s_waitcnt lgkmcnt(0)
	ds_read_b128 v[100:103], v0 offset:96
	ds_read_b128 v[104:107], v0 offset:64
	ds_read_b128 v[108:111], v0 offset:32
	ds_read_b128 v[112:115], v0
	s_waitcnt lgkmcnt(3)
	v_pk_mul_f32 v[76:77], v[76:77], v[100:101]
	s_waitcnt lgkmcnt(2)
	v_pk_mul_f32 v[72:73], v[72:73], v[104:105]
	s_waitcnt lgkmcnt(1)
	v_pk_mul_f32 v[68:69], v[68:69], v[108:109]
	v_pk_mul_f32 v[78:79], v[78:79], v[102:103]
	v_pk_mul_f32 v[74:75], v[74:75], v[106:107]
	v_pk_mul_f32 v[70:71], v[70:71], v[110:111]
	s_waitcnt lgkmcnt(0)
	v_pk_mul_f32 v[66:67], v[66:67], v[114:115]
	v_pk_mul_f32 v[64:65], v[64:65], v[112:113]
	v_pk_mul_f32 v[60:61], v[60:61], v[100:101]
	v_pk_mul_f32 v[56:57], v[56:57], v[104:105]
	v_pk_mul_f32 v[52:53], v[52:53], v[108:109]
	v_pk_mul_f32 v[62:63], v[62:63], v[102:103]
	v_pk_mul_f32 v[58:59], v[58:59], v[106:107]
	v_pk_mul_f32 v[54:55], v[54:55], v[110:111]
	v_pk_mul_f32 v[50:51], v[50:51], v[114:115]
	v_pk_mul_f32 v[48:49], v[48:49], v[112:113]
	v_pk_mul_f32 v[44:45], v[44:45], v[100:101]
	v_pk_mul_f32 v[40:41], v[40:41], v[104:105]
	v_pk_mul_f32 v[36:37], v[36:37], v[108:109]
	v_pk_mul_f32 v[46:47], v[46:47], v[102:103]
	v_pk_mul_f32 v[42:43], v[42:43], v[106:107]
	v_pk_mul_f32 v[38:39], v[38:39], v[110:111]
	v_pk_mul_f32 v[34:35], v[34:35], v[114:115]
	v_pk_mul_f32 v[32:33], v[32:33], v[112:113]
	v_pk_mul_f32 v[28:29], v[28:29], v[100:101]
	v_pk_mul_f32 v[24:25], v[24:25], v[104:105]
	v_pk_mul_f32 v[20:21], v[20:21], v[108:109]
	v_pk_mul_f32 v[30:31], v[30:31], v[102:103]
	v_pk_mul_f32 v[26:27], v[26:27], v[106:107]
	v_pk_mul_f32 v[22:23], v[22:23], v[110:111]
	v_pk_mul_f32 v[18:19], v[18:19], v[114:115]
	v_pk_mul_f32 v[16:17], v[16:17], v[112:113]
.Lstg_283:
	s_add_i32 s72, s76, 0x2000
	s_cmpk_lg_i32 s76, 0x4000
	s_cselect_b32 s87, s72, 0
	v_mfma_f32_32x32x16_bf16 v[112:127], v[96:99], v[184:187], v[80:95]
	v_add_f32_e32 v100, v144, v145
	v_add_f32_e32 v100, v146, v100
	v_add_f32_e32 v100, v147, v100
	s_lshl_b32 s72, s78, 1
	v_add_f32_e32 v100, v148, v100
	v_add_u32_e32 v233, s72, v245
	v_add_f32_e32 v96, v149, v100
	v_cvt_pk_bf16_f32 v188, v144, v145
	v_cvt_pk_bf16_f32 v189, v146, v147
	s_nop 0
	v_add_f32_e32 v96, v150, v96
	v_add_f32_e32 v96, v151, v96
	v_add_f32_e32 v96, v152, v96
	v_add_f32_e32 v144, v153, v96
	v_mfma_f32_32x32x16_bf16 v[96:111], v[10:13], v[184:187], v[80:95]
	v_cvt_pk_bf16_f32 v190, v148, v149
	v_cvt_pk_bf16_f32 v191, v150, v151
	v_mfma_f32_32x32x16_bf16 v[112:127], v[204:207], v[176:179], v[112:127]
	v_add_f32_e32 v10, v154, v144
	v_add_f32_e32 v10, v155, v10
	v_add_f32_e32 v10, v156, v10
	v_add_f32_e32 v10, v157, v10
	v_cvt_pk_bf16_f32 v180, v152, v153
	v_cvt_pk_bf16_f32 v181, v154, v155
	v_mfma_f32_32x32x16_bf16 v[96:111], v[192:195], v[176:179], v[96:111]
	v_add_f32_e32 v10, v158, v10
	v_add_f32_e32 v10, v159, v10
	v_add_f32_e32 v10, v128, v10
	v_add_f32_e32 v10, v129, v10
	v_cvt_pk_bf16_f32 v182, v156, v157
	v_cvt_pk_bf16_f32 v183, v158, v159
	v_mfma_f32_32x32x16_bf16 v[112:127], v[200:203], v[172:175], v[112:127]
	v_add_f32_e32 v10, v130, v10
	v_add_f32_e32 v10, v131, v10
	v_add_f32_e32 v10, v132, v10
	v_add_f32_e32 v10, v133, v10
	v_cvt_pk_bf16_f32 v168, v128, v129
	v_cvt_pk_bf16_f32 v169, v130, v131
	v_mfma_f32_32x32x16_bf16 v[96:111], v[6:9], v[172:175], v[96:111]
	v_add_f32_e32 v6, v134, v10
	v_add_f32_e32 v6, v135, v6
	v_add_f32_e32 v6, v136, v6
	v_add_f32_e32 v10, v137, v6
	v_cvt_pk_bf16_f32 v170, v132, v133
	v_cvt_pk_bf16_f32 v171, v134, v135
	ds_read_b64_tr_b16 v[6:7], v233 offset:24576
	ds_read_b64_tr_b16 v[8:9], v233 offset:25088
	v_mfma_f32_32x32x16_bf16 v[112:127], v[196:199], v[164:167], v[112:127]
	v_add_f32_e32 v10, v138, v10
	v_add_f32_e32 v10, v139, v10
	v_add_f32_e32 v10, v140, v10
	v_add_f32_e32 v128, v141, v10
	v_cvt_pk_bf16_f32 v160, v136, v137
	v_cvt_pk_bf16_f32 v161, v138, v139
	ds_read_b64_tr_b16 v[10:11], v233 offset:28672
	ds_read_b64_tr_b16 v[12:13], v233 offset:29184
	v_mfma_f32_32x32x16_bf16 v[96:111], v[2:5], v[164:167], v[96:111]
	ds_read_b64_tr_b16 v[144:145], v233 offset:32768
	ds_read_b64_tr_b16 v[146:147], v233 offset:33280
	ds_read_b64_tr_b16 v[148:149], v233 offset:36864
	ds_read_b64_tr_b16 v[150:151], v233 offset:37376
	ds_read_b64_tr_b16 v[152:153], v233 offset:25600
	ds_read_b64_tr_b16 v[154:155], v233 offset:26112
	ds_read_b64_tr_b16 v[156:157], v233 offset:29696
	ds_read_b64_tr_b16 v[158:159], v233 offset:30208
	v_add_f32_e32 v2, v142, v128
	v_add_f32_e32 v2, v143, v2
	v_add_f32_e32 v4, 0, v2
	v_cvt_pk_bf16_f32 v162, v140, v141
	v_cvt_pk_bf16_f32 v163, v142, v143
	v_max_f32_e32 v2, v113, v113
	v_max_f32_e32 v3, v112, v112
	v_max_f32_e32 v2, v3, v2
	v_max3_f32 v3, v114, v115, v97
	v_max3_f32 v2, v2, v96, v98
	v_max3_f32 v2, v2, v99, v116
	v_max3_f32 v3, v3, v118, v119
	v_max3_f32 v2, v2, v117, v100
	v_max3_f32 v3, v3, v102, v103
	v_max3_f32 v2, v2, v101, v120
	v_max3_f32 v3, v3, v122, v123
	v_max3_f32 v2, v2, v121, v104
	v_max3_f32 v3, v3, v106, v107
	v_max3_f32 v2, v2, v105, v124
	v_max3_f32 v3, v3, v126, v127
	v_max3_f32 v2, v2, v125, v108
	v_max3_f32 v3, v3, v110, v111
	v_max3_f32 v2, v2, v109, v3
	v_mov_b32_e32 v3, v2
	s_nop 1
	v_permlane32_swap_b32_e32 v2, v3
	v_max_f32_e32 v3, v3, v3
	v_max_f32_e32 v2, v2, v2
	v_max_f32_e32 v2, v2, v3
	v_cmp_lt_f32_e32 vcc, s96, v2
	s_cmp_lg_u64 vcc, 0
	v_add_f32_e32 v231, v212, v4
	s_cselect_b64 s[72:73], -1, 0
	s_cbranch_vccnz .Lstg_291
.Lstg_284:
	s_waitcnt vmcnt(0)
	s_barrier
	v_lshl_add_u64 v[2:3], v[14:15], 0, s[52:53]
	s_add_i32 vcc_lo, s76, s64
	s_mov_b32 vcc_hi, m0
	s_mov_b32 m0, vcc_lo
	s_nop 0
	global_load_lds_dwordx4 v[2:3], off
	s_mov_b32 m0, vcc_hi
	v_lshl_add_u64 v[2:3], v[208:209], 0, s[50:51]
	s_lshl_b32 vcc_lo, s87, 1
	s_add_i32 vcc_lo, vcc_lo, s63
	s_mov_b32 vcc_hi, m0
	s_mov_b32 m0, vcc_lo
	s_nop 0
	global_load_lds_dwordx4 v[2:3], off
	s_mov_b32 m0, vcc_hi
	v_lshl_add_u64 v[2:3], v[210:211], 0, s[50:51]
	s_addk_i32 vcc_lo, 0x2000
	s_mov_b32 vcc_hi, m0
	s_mov_b32 m0, vcc_lo
	s_nop 0
	global_load_lds_dwordx4 v[2:3], off
	s_mov_b32 m0, vcc_hi
	s_waitcnt lgkmcnt(10)
	v_mfma_f32_32x32x16_bf16 v[64:79], v[188:191], v[6:9], v[64:79]
	v_exp_f32_e32 v112, v112
	v_exp_f32_e32 v113, v113
	s_waitcnt lgkmcnt(8)
	v_mfma_f32_32x32x16_bf16 v[48:63], v[188:191], v[10:13], v[48:63]
	v_exp_f32_e32 v114, v114
	v_exp_f32_e32 v115, v115
	v_add_u32_e32 v10, s87, v225
	ds_read_b128 v[220:223], v10
	ds_read_b128 v[212:215], v10 offset:512
	s_waitcnt lgkmcnt(8)
	v_mfma_f32_32x32x16_bf16 v[32:47], v[188:191], v[144:147], v[32:47]
	v_exp_f32_e32 v116, v116
	v_exp_f32_e32 v117, v117
	ds_read_b64_tr_b16 v[144:145], v233 offset:33792
	ds_read_b64_tr_b16 v[146:147], v233 offset:34304
	s_waitcnt lgkmcnt(8)
	v_mfma_f32_32x32x16_bf16 v[16:31], v[188:191], v[148:151], v[16:31]
	v_exp_f32_e32 v118, v118
	v_exp_f32_e32 v119, v119
	ds_read_b128 v[216:219], v10 offset:2048
	ds_read_b128 v[204:207], v10 offset:2560
	ds_read_b64_tr_b16 v[148:149], v233 offset:37888
	ds_read_b64_tr_b16 v[150:151], v233 offset:38400
	s_waitcnt lgkmcnt(10)
	v_mfma_f32_32x32x16_bf16 v[64:79], v[180:183], v[152:155], v[64:79]
	v_exp_f32_e32 v120, v120
	v_exp_f32_e32 v121, v121
	ds_read_b64_tr_b16 v[152:153], v233 offset:26624
	ds_read_b64_tr_b16 v[154:155], v233 offset:27136
	s_waitcnt lgkmcnt(10)
	v_mfma_f32_32x32x16_bf16 v[48:63], v[180:183], v[156:159], v[48:63]
	v_exp_f32_e32 v122, v122
	v_exp_f32_e32 v123, v123
	ds_read_b128 v[208:211], v10 offset:4096
	ds_read_b128 v[200:203], v10 offset:4608
	ds_read_b64_tr_b16 v[156:157], v233 offset:30720
	ds_read_b64_tr_b16 v[158:159], v233 offset:31232
	s_waitcnt lgkmcnt(10)
	v_mfma_f32_32x32x16_bf16 v[32:47], v[180:183], v[144:147], v[32:47]
	v_exp_f32_e32 v124, v124
	v_exp_f32_e32 v125, v125
	ds_read_b64_tr_b16 v[144:145], v233 offset:34816
	ds_read_b64_tr_b16 v[146:147], v233 offset:35328
	s_waitcnt lgkmcnt(8)
	v_mfma_f32_32x32x16_bf16 v[16:31], v[180:183], v[148:151], v[16:31]
	v_exp_f32_e32 v126, v126
	v_exp_f32_e32 v127, v127
	ds_read_b128 v[196:199], v10 offset:6144
	ds_read_b128 v[192:195], v10 offset:6656
	ds_read_b64_tr_b16 v[148:149], v233 offset:38912
	ds_read_b64_tr_b16 v[150:151], v233 offset:39424
	s_waitcnt lgkmcnt(10)
	v_mfma_f32_32x32x16_bf16 v[64:79], v[168:171], v[152:155], v[64:79]
	v_exp_f32_e32 v96, v96
	v_exp_f32_e32 v97, v97
	ds_read_b64_tr_b16 v[152:153], v233 offset:27648
	ds_read_b64_tr_b16 v[154:155], v233 offset:28160
	s_waitcnt lgkmcnt(8)
	v_mfma_f32_32x32x16_bf16 v[48:63], v[168:171], v[156:159], v[48:63]
	v_exp_f32_e32 v98, v98
	v_exp_f32_e32 v99, v99
	ds_read_b64_tr_b16 v[156:157], v233 offset:31744
	ds_read_b64_tr_b16 v[158:159], v233 offset:32256
	s_waitcnt lgkmcnt(8)
	v_mfma_f32_32x32x16_bf16 v[32:47], v[168:171], v[144:147], v[32:47]
	v_exp_f32_e32 v100, v100
	v_exp_f32_e32 v101, v101
	ds_read_b64_tr_b16 v[144:145], v233 offset:35840
	ds_read_b64_tr_b16 v[146:147], v233 offset:36352
	s_waitcnt lgkmcnt(6)
	v_mfma_f32_32x32x16_bf16 v[16:31], v[168:171], v[148:151], v[16:31]
	v_exp_f32_e32 v102, v102
	v_exp_f32_e32 v103, v103
	ds_read_b64_tr_b16 v[148:149], v233 offset:39936
	ds_read_b64_tr_b16 v[150:151], v233 offset:40448
	s_waitcnt lgkmcnt(6)
	v_mfma_f32_32x32x16_bf16 v[64:79], v[160:163], v[152:155], v[64:79]
	v_exp_f32_e32 v104, v104
	v_exp_f32_e32 v105, v105
	s_waitcnt lgkmcnt(4)
	v_mfma_f32_32x32x16_bf16 v[48:63], v[160:163], v[156:159], v[48:63]
	v_exp_f32_e32 v106, v106
	v_exp_f32_e32 v107, v107
	s_waitcnt lgkmcnt(2)
	v_mfma_f32_32x32x16_bf16 v[32:47], v[160:163], v[144:147], v[32:47]
	v_exp_f32_e32 v108, v108
	v_exp_f32_e32 v109, v109
	s_waitcnt lgkmcnt(0)
	v_mfma_f32_32x32x16_bf16 v[16:31], v[160:163], v[148:151], v[16:31]
	v_exp_f32_e32 v110, v110
	v_exp_f32_e32 v111, v111
	s_waitcnt lgkmcnt(0)
	s_andn2_b64 vcc, exec, s[72:73]
	s_cbranch_vccnz .Lstg_286

; #define WAIT_BAR(N) asm volatile("s_waitcnt vmcnt(" #N ") lgkmcnt(0)\n\ts_barrier":::"memory")
;   #define RESC() do{ if(resc){ asm volatile("s_waitcnt lgkmcnt(0)":::"memory"); \
;       _Pragma("unroll") for(int d_=0;d_<2;++d_) _Pragma("unroll") for(int r=0;r<16;++r)o[d_][r]*=wsf[crow(r,hi)]; } }while(0)
;   #define ROT() do{sl_prev=sl_cur;sl_cur=sl_next;sl_next=(sl_next==(NSLOT-1)*SLOTB)?0:sl_next+SLOTB;}while(0)
; #define WAIT_BAR(N) asm volatile("s_waitcnt vmcnt(" #N ") lgkmcnt(0)\n\ts_barrier":::"memory")
;   #define RESC() do{ if(resc){ asm volatile("s_waitcnt lgkmcnt(0)":::"memory"); \
;       _Pragma("unroll") for(int d_=0;d_<4;++d_) _Pragma("unroll") for(int r=0;r<16;++r)o[d_][r]*=wsf[crow(r,hi)]; } }while(0)
;   #define ROT() do{sl_prev=sl_cur;sl_cur=sl_next;sl_next=(sl_next==(NSLOT-1)*SLOTB)?0:sl_next+SLOTB;}while(0)
; template<int THRL,bool BIAS> __device__ __forceinline__ void attn_unit(int b,int qb,const bf16*Q,const bf16*__restrict__ K,const bf16*__restrict__ V,bf16*O,const float*__restrict__ biasg,char*shm,const int tid_in,const bool comb,const bf16*O0,const float lam,const float osc,const float*__restrict__ ...
;     ...
;   f32x16 pA0,pA1,pB0,pB1;
;   int sl_prev=0,sl_cur=0,sl_next=SLOTB;
;     ...
;   for(;t+5<NT;t+=2){
;     STEP(pB0,pB1,pA0,pA1,t,true,true,true);     WAIT_BAR(3); RESC(); ROT();
;     STEP(pA0,pA1,pB0,pB1,t+1,true,true,true);   WAIT_BAR(3); RESC(); ROT();
;   }
	s_waitcnt lgkmcnt(0)
	ds_read_b128 v[2:5], v0 offset:96
	ds_read_b128 v[6:9], v0 offset:64
	ds_read_b128 v[10:13], v0 offset:32
	ds_read_b128 v[128:131], v0
	s_waitcnt lgkmcnt(3)
	v_pk_mul_f32 v[76:77], v[76:77], v[2:3]
	s_waitcnt lgkmcnt(2)
	v_pk_mul_f32 v[72:73], v[72:73], v[6:7]
	s_waitcnt lgkmcnt(1)
	v_pk_mul_f32 v[68:69], v[68:69], v[10:11]
	v_pk_mul_f32 v[78:79], v[78:79], v[4:5]
	v_pk_mul_f32 v[74:75], v[74:75], v[8:9]
	v_pk_mul_f32 v[70:71], v[70:71], v[12:13]
	s_waitcnt lgkmcnt(0)
	v_pk_mul_f32 v[66:67], v[66:67], v[130:131]
	v_pk_mul_f32 v[64:65], v[64:65], v[128:129]
	v_pk_mul_f32 v[60:61], v[60:61], v[2:3]
	v_pk_mul_f32 v[56:57], v[56:57], v[6:7]
	v_pk_mul_f32 v[52:53], v[52:53], v[10:11]
	v_pk_mul_f32 v[62:63], v[62:63], v[4:5]
	v_pk_mul_f32 v[58:59], v[58:59], v[8:9]
	v_pk_mul_f32 v[54:55], v[54:55], v[12:13]
	v_pk_mul_f32 v[50:51], v[50:51], v[130:131]
	v_pk_mul_f32 v[48:49], v[48:49], v[128:129]
	v_pk_mul_f32 v[44:45], v[44:45], v[2:3]
	v_pk_mul_f32 v[40:41], v[40:41], v[6:7]
	v_pk_mul_f32 v[36:37], v[36:37], v[10:11]
	v_pk_mul_f32 v[46:47], v[46:47], v[4:5]
	v_pk_mul_f32 v[42:43], v[42:43], v[8:9]
	v_pk_mul_f32 v[38:39], v[38:39], v[12:13]
	v_pk_mul_f32 v[34:35], v[34:35], v[130:131]
	v_pk_mul_f32 v[32:33], v[32:33], v[128:129]
	v_pk_mul_f32 v[28:29], v[28:29], v[2:3]
	v_pk_mul_f32 v[24:25], v[24:25], v[6:7]
	v_pk_mul_f32 v[20:21], v[20:21], v[10:11]
	v_pk_mul_f32 v[30:31], v[30:31], v[4:5]
	v_pk_mul_f32 v[26:27], v[26:27], v[8:9]
	v_pk_mul_f32 v[22:23], v[22:23], v[12:13]
	v_pk_mul_f32 v[18:19], v[18:19], v[130:131]
	v_pk_mul_f32 v[16:17], v[16:17], v[128:129]
.Lstg_286:
	s_add_i32 s72, s87, 0x2000
	s_cmpk_lg_i32 s87, 0x4000
	s_cselect_b32 s88, s72, 0
	s_add_i32 s72, s77, 2
	s_add_u32 s6, s6, 0xc0000
	s_addc_u32 s7, s7, 0
	s_cmp_ge_u32 s72, s60
	s_cbranch_scc1 .Lstg_exit_lag

	s_mov_b32 s77, s72
	s_mov_b32 s72, s76
	s_mov_b32 s78, s87
	s_mov_b32 s76, s88
	s_branch .Lstg_280
.Lstg_288:
	v_max_f32_e32 v10, v10, v10
	v_max_f32_e32 v10, 0, v10
	v_exp_f32_e64 v11, -v10
	v_add_f32_e32 v224, v224, v10
	v_xor_b32_e32 v80, 0x80000000, v224
	v_mov_b32_e32 v81, v80
	v_mov_b32_e32 v82, v80
	v_mov_b32_e32 v83, v80
	v_mov_b32_e32 v84, v80
	v_mov_b32_e32 v85, v80
	v_mov_b32_e32 v86, v80
	v_mov_b32_e32 v87, v80
	v_mov_b32_e32 v88, v80
	v_mov_b32_e32 v89, v80
	v_mov_b32_e32 v90, v80
	v_mov_b32_e32 v91, v80
	v_mov_b32_e32 v92, v80
	v_mov_b32_e32 v93, v80
	v_mov_b32_e32 v94, v80
	v_mov_b32_e32 v95, v80
	s_and_saveexec_b64 s[74:75], s[4:5]

	ds_write_b32 v241, v11

	s_or_b64 exec, exec, s[74:75]
	v_sub_f32_e32 v159, v159, v10
	v_sub_f32_e32 v158, v158, v10
	v_sub_f32_e32 v157, v157, v10
	v_sub_f32_e32 v156, v156, v10
	v_sub_f32_e32 v155, v155, v10
	v_sub_f32_e32 v154, v154, v10
	v_sub_f32_e32 v153, v153, v10
	v_sub_f32_e32 v152, v152, v10
	v_sub_f32_e32 v151, v151, v10
	v_sub_f32_e32 v150, v150, v10
	v_sub_f32_e32 v149, v149, v10
	v_sub_f32_e32 v148, v148, v10
	v_sub_f32_e32 v147, v147, v10
	v_sub_f32_e32 v146, v146, v10
	v_sub_f32_e32 v145, v145, v10
	v_sub_f32_e32 v144, v144, v10
	v_sub_f32_e32 v143, v143, v10
	v_sub_f32_e32 v142, v142, v10
	v_sub_f32_e32 v141, v141, v10
	v_sub_f32_e32 v140, v140, v10
	v_sub_f32_e32 v139, v139, v10
	v_sub_f32_e32 v138, v138, v10
	v_sub_f32_e32 v137, v137, v10
	v_sub_f32_e32 v136, v136, v10
	v_sub_f32_e32 v135, v135, v10
	v_sub_f32_e32 v134, v134, v10
	v_sub_f32_e32 v133, v133, v10
	v_sub_f32_e32 v132, v132, v10
	v_sub_f32_e32 v131, v131, v10
	v_sub_f32_e32 v130, v130, v10
	v_sub_f32_e32 v129, v129, v10
	v_sub_f32_e32 v128, v128, v10
	v_mul_f32_e32 v212, v212, v11
	s_branch .Lstg_281
.Lstg_291:
	v_max_f32_e32 v2, v2, v2
	v_max_f32_e32 v2, 0, v2
	v_exp_f32_e64 v3, -v2
	v_add_f32_e32 v224, v224, v2
	v_xor_b32_e32 v80, 0x80000000, v224
	v_mov_b32_e32 v81, v80
	v_mov_b32_e32 v82, v80
	v_mov_b32_e32 v83, v80
	v_mov_b32_e32 v84, v80
	v_mov_b32_e32 v85, v80
	v_mov_b32_e32 v86, v80
	v_mov_b32_e32 v87, v80
	v_mov_b32_e32 v88, v80
	v_mov_b32_e32 v89, v80
	v_mov_b32_e32 v90, v80
	v_mov_b32_e32 v91, v80
	v_mov_b32_e32 v92, v80
	v_mov_b32_e32 v93, v80
	v_mov_b32_e32 v94, v80
	v_mov_b32_e32 v95, v80
	s_and_saveexec_b64 s[74:75], s[4:5]

	ds_write_b32 v241, v3

; #define WAIT_BAR(N) asm volatile("s_waitcnt vmcnt(" #N ") lgkmcnt(0)\n\ts_barrier":::"memory")
;   #define RESC() do{ if(resc){ asm volatile("s_waitcnt lgkmcnt(0)":::"memory"); \
;       _Pragma("unroll") for(int d_=0;d_<2;++d_) _Pragma("unroll") for(int r=0;r<16;++r)o[d_][r]*=wsf[crow(r,hi)]; } }while(0)
;   #define ROT() do{sl_prev=sl_cur;sl_cur=sl_next;sl_next=(sl_next==(NSLOT-1)*SLOTB)?0:sl_next+SLOTB;}while(0)
;   #define ENDW(tt) do{ if((tt)+3<NT){WAIT_BAR(2);} else if((tt)+2<NT){WAIT_BAR(1);} else {WAIT_BAR(0);} }while(0)
; #define WAIT_BAR(N) asm volatile("s_waitcnt vmcnt(" #N ") lgkmcnt(0)\n\ts_barrier":::"memory")
;   #define RESC() do{ if(resc){ asm volatile("s_waitcnt lgkmcnt(0)":::"memory"); \
;       _Pragma("unroll") for(int d_=0;d_<4;++d_) _Pragma("unroll") for(int r=0;r<16;++r)o[d_][r]*=wsf[crow(r,hi)]; } }while(0)
;   #define ROT() do{sl_prev=sl_cur;sl_cur=sl_next;sl_next=(sl_next==(NSLOT-1)*SLOTB)?0:sl_next+SLOTB;}while(0)
;   #define ENDW(tt) do{ if((tt)+3<NT){WAIT_BAR(3);} else if((tt)+2<NT){WAIT_BAR(2);} else {WAIT_BAR(0);} }while(0)
; template<int THRL,bool BIAS> __device__ __forceinline__ void attn_unit(int b,int qb,const bf16*Q,const bf16*__restrict__ K,const bf16*__restrict__ V,bf16*O,const float*__restrict__ biasg,char*shm,const int tid_in,const bool comb,const bf16*O0,const float lam,const float osc,const float*__restrict__ ...
;     ...
;   for(;t+5<NT;t+=2){
;     STEP(pB0,pB1,pA0,pA1,t,true,true,true);     WAIT_BAR(3); RESC(); ROT();
;     STEP(pA0,pA1,pB0,pB1,t+1,true,true,true);   WAIT_BAR(3); RESC(); ROT();
;   }
;     ...
;   for(;t+1<NT;t+=2){
;     STEP(pB0,pB1,pA0,pA1,t,(t+3<NT),(t+1<NT),(t+1<NT));       ENDW(t);   RESC(); ROT();
;     STEP(pA0,pA1,pB0,pB1,t+1,(t+4<NT),(t+2<NT),(t+2<NT));     ENDW(t+1); RESC(); ROT();
;   }
;   STEP(pB0,pB1,pA0,pA1,NT-1,false,false,false); RESC();
	s_or_b64 exec, exec, s[74:75]
	v_sub_f32_e32 v127, v127, v2
	v_sub_f32_e32 v126, v126, v2
	v_sub_f32_e32 v125, v125, v2
	v_sub_f32_e32 v124, v124, v2
	v_sub_f32_e32 v123, v123, v2
	v_sub_f32_e32 v122, v122, v2
	v_sub_f32_e32 v121, v121, v2
	v_sub_f32_e32 v120, v120, v2
	v_sub_f32_e32 v119, v119, v2
	v_sub_f32_e32 v118, v118, v2
	v_sub_f32_e32 v117, v117, v2
	v_sub_f32_e32 v116, v116, v2
	v_sub_f32_e32 v115, v115, v2
	v_sub_f32_e32 v114, v114, v2
	v_sub_f32_e32 v113, v113, v2
	v_sub_f32_e32 v112, v112, v2
	v_sub_f32_e32 v111, v111, v2
	v_sub_f32_e32 v110, v110, v2
	v_sub_f32_e32 v109, v109, v2
	v_sub_f32_e32 v108, v108, v2
	v_sub_f32_e32 v107, v107, v2
	v_sub_f32_e32 v106, v106, v2
	v_sub_f32_e32 v105, v105, v2
	v_sub_f32_e32 v104, v104, v2
	v_sub_f32_e32 v103, v103, v2
	v_sub_f32_e32 v102, v102, v2
	v_sub_f32_e32 v101, v101, v2
	v_sub_f32_e32 v100, v100, v2
	v_sub_f32_e32 v99, v99, v2
	v_sub_f32_e32 v98, v98, v2
	v_sub_f32_e32 v97, v97, v2
	v_sub_f32_e32 v96, v96, v2
	v_mul_f32_e32 v231, v231, v3
	s_branch .Lstg_284
.Lstg_exit_lead:
	s_barrier
	s_branch .LBB0_306
.Lstg_exit_lag:
	s_waitcnt lgkmcnt(0)
	s_barrier
	s_branch .LBB0_306
